# step 0 without vmcnt waits (on top of batched K0 reads): V0 DMA of a prefetched unit is not drained mid-step
# baseline (speedup 1.0000x reference)
;   #define CINIT(C0,C1,btl) do{ const float b_=(btl); _Pragma("unroll") for(int r=0;r<16;++r){ C0[r]=__builtin_fmaf(s2,(float)((r&3)+8*(r>>2)),b_); C1[r]=__builtin_fmaf(s2,(float)((r&3)+8*(r>>2)+32),b_);} }while(0)
;   #define CMASK(P0,P1,t) do{ if(WIN||(t)>=NT-4)gmask(P0,P1,64*(t),qrel,hi,WIN);}while(0)
;   #define CMASK(P0,P1,t) do{}while(0)
;   #define CMASK(P0,P1,t) do{ if(WIN||(t)>=NT-4)gmask(P0,P1,64*(t),qrel,hi,WIN);}while(0)
; __device__ __forceinline__ void qkt(f32x16&p0,f32x16&p1,const char*Kslot,const bf16x8*qr,int r32,int hi){
;   const char*kb=Kslot+hi*1024+r32*16;
;   #pragma unroll
;   for(int d0=0;d0<4;++d0){
;     const bf16x8 b0=*reinterpret_cast<const bf16x8*>(kb+d0*2048);
;     const bf16x8 b1=*reinterpret_cast<const bf16x8*>(kb+d0*2048+512);
;     p0=__builtin_amdgcn_mfma_f32_32x32x16_bf16(b0,qr[d0],p0,0,0,0);p1=__builtin_amdgcn_mfma_f32_32x32x16_bf16(b1,qr[d0],p1,0,0,0);}
; }
; template<int THRL> __device__ __forceinline__ void attn_unit(long rowbase,int qb,int t0,bool WIN,bool NOMAX,const bf16*Qc,const bf16*__restrict__ Kc,const bf16*__restrict__ Vc,bf16*Oc,float s2,float sink2,char*shm,
;     bf16x8 (&qr)[4],bool pref,const bf16*qkvb,int vn,int in_){
;     ...
;   CINIT(pA0,pA1,-qb2); qkt(pA0,pA1,Kbase,qr,r32,hi);asm volatile("s_nop 15\n\ts_nop 7":"+v"(pA0),"+v"(pA1));CMASK(pA0,pA1,0);
.LBB0_265:
	s_sub_i32 s38, s4, s45
	v_or_b32_e32 v18, s38, v180
	v_lshlrev_b32_e32 v230, 2, v181
	v_add_u32_e32 v223, s2, v18
	v_sub_u32_e32 v18, v223, v230
	v_cvt_f32_i32_e32 v19, v18
	v_lshlrev_b32_e32 v18, 10, v181
	v_lshlrev_b32_e32 v20, 4, v180
	v_add3_u32 v231, 0, v18, v20
	v_mul_f32_e32 v184, 0x3fb8aa3b, v34
	ds_read_b128 v[34:37], v231
	ds_read_b128 v[52:55], v231 offset:512
	ds_read_b128 v[56:59], v231 offset:2048
	ds_read_b128 v[60:63], v231 offset:2560
	ds_read_b128 v[64:67], v231 offset:4096
	ds_read_b128 v[68:71], v231 offset:4608
	ds_read_b128 v[72:75], v231 offset:6144
	ds_read_b128 v[76:79], v231 offset:6656
	v_mul_f32_e64 v186, v184, -v19
	v_fma_f32 v18, 0, v184, v186
	v_fma_f32 v19, v184, -v19, v184
	v_pk_fma_f32 v[20:21], v[184:185], s[8:9], v[186:187] op_sel_hi:[0,1,0]
	v_pk_fma_f32 v[22:23], v[184:185], s[10:11], v[186:187] op_sel_hi:[0,1,0]
	v_pk_fma_f32 v[24:25], v[184:185], s[12:13], v[186:187] op_sel_hi:[0,1,0]
	v_pk_fma_f32 v[26:27], v[184:185], s[14:15], v[186:187] op_sel_hi:[0,1,0]
	v_pk_fma_f32 v[28:29], v[184:185], s[16:17], v[186:187] op_sel_hi:[0,1,0]
	v_pk_fma_f32 v[30:31], v[184:185], s[18:19], v[186:187] op_sel_hi:[0,1,0]
	v_pk_fma_f32 v[32:33], v[184:185], s[20:21], v[186:187] op_sel_hi:[0,1,0]
	v_pk_fma_f32 v[48:49], v[184:185], s[22:23], v[186:187] op_sel_hi:[0,1,0]
	v_pk_fma_f32 v[46:47], v[184:185], s[24:25], v[186:187] op_sel_hi:[0,1,0]
	s_waitcnt lgkmcnt(7)
	v_mfma_f32_32x32x16_bf16 v[18:33], v[34:37], v[2:5], v[18:33]
	v_fma_f32 v44, v184, s26, v186
	v_fma_f32 v45, v184, s27, v186
	v_fma_f32 v42, v184, s28, v186
	v_fma_f32 v43, v184, s29, v186
	v_fma_f32 v40, v184, s30, v186
	v_fma_f32 v41, v184, s31, v186
	v_pk_fma_f32 v[38:39], v[184:185], s[34:35], v[186:187] op_sel_hi:[0,1,0]
	v_pk_fma_f32 v[36:37], v[184:185], s[36:37], v[186:187] op_sel_hi:[0,1,0]
	v_pk_fma_f32 v[34:35], v[184:185], s[92:93], v[186:187] op_sel_hi:[0,1,0]
	s_addk_i32 s4, 0x100
	s_lshr_b32 s4, s4, 6
	s_waitcnt lgkmcnt(6)
	v_mfma_f32_32x32x16_bf16 v[34:49], v[52:55], v[2:5], v[34:49]
	s_sub_i32 s4, s4, s48
	s_cmp_lg_u32 s62, 0
	s_cselect_b32 s4, 4, s4
	s_cmp_lt_i32 s4, 5
	s_cselect_b64 s[38:39], -1, 0
	s_or_b64 s[38:39], s[62:63], s[38:39]
	s_andn2_b64 vcc, exec, s[38:39]
	v_add_u32_e32 v224, 0xffffff80, v223
	s_waitcnt lgkmcnt(5)
	v_mfma_f32_32x32x16_bf16 v[18:33], v[56:59], v[6:9], v[18:33]
	s_waitcnt lgkmcnt(4)
	v_mfma_f32_32x32x16_bf16 v[34:49], v[60:63], v[6:9], v[34:49]
	s_waitcnt lgkmcnt(3)
	v_mfma_f32_32x32x16_bf16 v[18:33], v[64:67], v[10:13], v[18:33]
	s_waitcnt lgkmcnt(2)
	v_mfma_f32_32x32x16_bf16 v[34:49], v[68:71], v[10:13], v[34:49]
	s_waitcnt lgkmcnt(1)
	v_mfma_f32_32x32x16_bf16 v[18:33], v[72:75], v[14:17], v[18:33]
	s_waitcnt lgkmcnt(0)
	v_mfma_f32_32x32x16_bf16 v[34:49], v[76:79], v[14:17], v[34:49]
	v_cndmask_b32_e64 v52, 0, 1, s[62:63]
	v_cmp_ne_u32_e64 s[38:39], 1, v52
	s_nop 15
	s_nop 7
	s_cbranch_vccnz .LBB0_330
	v_sub_u32_e32 v52, v223, v230
	s_nop 0
	v_readfirstlane_b32 s40, v52
	s_cmp_gt_i32 s40, 66
	s_cbranch_scc1 .Lmy_mk_c_s0
	v_cmp_le_i32_e32 vcc, 0, v52
	v_cndmask_b32_e32 v18, v217, v18, vcc
	v_cmp_le_i32_e32 vcc, 32, v52
	v_cndmask_b32_e32 v34, v217, v34, vcc
	v_cmp_le_i32_e32 vcc, 1, v52
	v_cndmask_b32_e32 v19, v217, v19, vcc
	v_cmp_le_i32_e32 vcc, 33, v52
	v_cndmask_b32_e32 v35, v217, v35, vcc
	v_cmp_le_i32_e32 vcc, 2, v52
	v_cndmask_b32_e32 v20, v217, v20, vcc
	v_cmp_le_i32_e32 vcc, 34, v52
	v_cndmask_b32_e32 v36, v217, v36, vcc
	v_cmp_le_i32_e32 vcc, 3, v52
	v_cndmask_b32_e32 v21, v217, v21, vcc
	v_cmp_le_i32_e32 vcc, 35, v52
	v_cndmask_b32_e32 v37, v217, v37, vcc
	v_cmp_le_i32_e32 vcc, 8, v52
	v_cndmask_b32_e32 v22, v217, v22, vcc
	v_cmp_le_i32_e32 vcc, 40, v52
	v_cndmask_b32_e32 v38, v217, v38, vcc
	v_cmp_le_i32_e32 vcc, 9, v52
	v_cndmask_b32_e32 v23, v217, v23, vcc
	v_cmp_le_i32_e32 vcc, 41, v52
	v_cndmask_b32_e32 v39, v217, v39, vcc
	v_cmp_le_i32_e32 vcc, 10, v52
	v_cndmask_b32_e32 v24, v217, v24, vcc
	v_cmp_le_i32_e32 vcc, 42, v52
	v_cndmask_b32_e32 v40, v217, v40, vcc
	v_cmp_le_i32_e32 vcc, 11, v52
	v_cndmask_b32_e32 v25, v217, v25, vcc
	v_cmp_le_i32_e32 vcc, 43, v52
	v_cndmask_b32_e32 v41, v217, v41, vcc
	v_cmp_le_i32_e32 vcc, 16, v52
	v_cndmask_b32_e32 v26, v217, v26, vcc
	v_cmp_le_i32_e32 vcc, 48, v52
	v_cndmask_b32_e32 v42, v217, v42, vcc
	v_cmp_le_i32_e32 vcc, 17, v52
	v_cndmask_b32_e32 v27, v217, v27, vcc
	v_cmp_le_i32_e32 vcc, 49, v52
	v_cndmask_b32_e32 v43, v217, v43, vcc
	v_cmp_le_i32_e32 vcc, 18, v52
	v_cndmask_b32_e32 v28, v217, v28, vcc
	v_cmp_le_i32_e32 vcc, 50, v52
	v_cndmask_b32_e32 v44, v217, v44, vcc
	v_cmp_le_i32_e32 vcc, 19, v52
	v_cndmask_b32_e32 v29, v217, v29, vcc
	v_cmp_le_i32_e32 vcc, 51, v52
	v_cndmask_b32_e32 v45, v217, v45, vcc
	v_cmp_le_i32_e32 vcc, 24, v52
	v_cndmask_b32_e32 v30, v217, v30, vcc
	v_cmp_le_i32_e32 vcc, 56, v52
	v_cndmask_b32_e32 v46, v217, v46, vcc
	v_cmp_le_i32_e32 vcc, 25, v52
	v_cndmask_b32_e32 v31, v217, v31, vcc
	v_cmp_le_i32_e32 vcc, 57, v52
	v_cndmask_b32_e32 v47, v217, v47, vcc
	v_cmp_le_i32_e32 vcc, 26, v52
	v_cndmask_b32_e32 v32, v217, v32, vcc
	v_cmp_le_i32_e32 vcc, 58, v52
	v_cndmask_b32_e32 v48, v217, v48, vcc
	v_cmp_le_i32_e32 vcc, 27, v52
	v_cndmask_b32_e32 v33, v217, v33, vcc
	v_cmp_le_i32_e32 vcc, 59, v52
	v_cndmask_b32_e32 v49, v217, v49, vcc

; #define WAIT_BAR(N) asm volatile("s_waitcnt vmcnt(" #N ") lgkmcnt(0)\n\ts_barrier":::"memory")
;   #define DMA_K(t,slot) glds16(ksrc+(long)(t)*KVBLK*PIN,(unsigned)__builtin_amdgcn_readfirstlane(kdst+(slot)))
; template<int THRL> __device__ __forceinline__ void attn_unit(long rowbase,int qb,int t0,bool WIN,bool NOMAX,const bf16*Qc,const bf16*__restrict__ Kc,const bf16*__restrict__ Vc,bf16*Oc,float s2,float sink2,char*shm,
;     bf16x8 (&qr)[4],bool pref,const bf16*qkvb,int vn,int in_){
;     ...
;   if(!pref){ DMA_K(2,2*SLOTB);
;     WAIT_BAR(3); }
.LBB0_354:
	s_cmp_lg_u32 0, -1
	s_cselect_b32 s38, 0, 0
	s_add_i32 s38, s38, s82
	v_lshl_add_u64 v[18:19], v[194:195], 0, s[0:1]
	s_addk_i32 s38, 0x4000
	s_mov_b32 s39, m0
	s_mov_b32 m0, s38
	s_nop 0
	global_load_lds_dwordx4 v[18:19], off
	s_mov_b32 m0, s39
	s_waitcnt vmcnt(1) lgkmcnt(0)
	s_barrier
	s_cbranch_execz .LBB0_264
	s_branch .LBB0_265
